# chunk loops skip the loop-top workgroup barrier on the back edge (needed only on entry)
# speedup vs baseline: 1.0074x; 1.0074x over previous
; #define LAS __attribute__((address_space(3)))
; __device__ __forceinline__ unsigned cvt_pk_bf16(float lo, float hi) { const f32x2_t v = {lo, hi}; const bf16x2_t b = __builtin_convertvector(v, bf16x2_t); return __builtin_bit_cast(unsigned, b); }
; #define LBAR() do { asm volatile("s_waitcnt lgkmcnt(0)" ::: "memory"); __builtin_amdgcn_s_barrier(); asm volatile("" ::: "memory"); } while (0)
; __device__ void rwkv_chunk_phase(const Params& p, int l, LAS unsigned char* lds) {
;     ...
;             LBAR();
;             {   const f32x4 yv = *(const LAS f32x4*)(y_s + tok * 64 + cg * 4);
;                 u32x2 wv2; wv2.x = cvt_pk_bf16(yv[0], yv[1]); wv2.y = cvt_pk_bf16(yv[2], yv[3]);
;                 *(u32x2*)(Y + (t0 + tokm) * 512 + h * 64 + cg * 4) = wv2; }
.LBB0_320:
	s_or_b64 exec, exec, s[24:25]
	s_waitcnt lgkmcnt(0)
	s_barrier
	s_nop 2
	ds_read_b128 v[32:35], v94 offset:29184
	s_add_i32 s65, s65, -1
	s_cmp_eq_u32 s62, 64
	s_mov_b32 s63, s62
	s_waitcnt lgkmcnt(0)
	v_cvt_pk_bf16_f32 v2, v32, v33
	v_lshlrev_b64 v[32:33], 10, v[58:59]
	v_cvt_pk_bf16_f32 v3, v34, v35
	v_lshl_add_u64 v[32:33], v[56:57], 0, v[32:33]
	global_store_dwordx2 v[32:33], v[2:3], off
	s_cbranch_scc1 .LBB0_242
	s_branch .Lrw_top

; #define LAS __attribute__((address_space(3)))
; __device__ __forceinline__ unsigned cvt_pk_bf16(float lo, float hi) { const f32x2_t v = {lo, hi}; const bf16x2_t b = __builtin_convertvector(v, bf16x2_t); return __builtin_bit_cast(unsigned, b); }
; #define LBAR() do { asm volatile("s_waitcnt lgkmcnt(0)" ::: "memory"); __builtin_amdgcn_s_barrier(); asm volatile("" ::: "memory"); } while (0)
; __device__ void rwkv_chunk_phase(const Params& p, int l, LAS unsigned char* lds) {
;     ...
;             for (int hf = 0; hf < 2; ++hf) { float fc[8], fp[8], fn[8]; unpack8(rc[hf], fc); unpack8(rp[hf], fp); unpack8(rn[hf], fn);
;                 const f32x4 m0 = *(const LAS f32x4*)(mu_s + cg * 16 + hf * 8), m1 = *(const LAS f32x4*)(mu_s + cg * 16 + hf * 8 + 4);
;                 f32x4 x0, x1;
; #pragma unroll
;                 for (int j = 0; j < 4; ++j) { x0[j] = fc[j] + m0[j] * (0.5f * (fp[j] + fn[j]) - fc[j]); x1[j] = fc[4 + j] + m1[j] * (0.5f * (fp[4 + j] + fn[4 + j]) - fc[4 + j]); }
;                 *(LAS f32x4*)(sh_s + tok * 256 + cg * 16 + hf * 8) = x0; *(LAS f32x4*)(sh_s + tok * 256 + cg * 16 + hf * 8 + 4) = x1; }
;             LBAR();
;             {   const int rt = wid >> 2, ct = wid & 3, row = rt * 16 + r16;
;                 const f32x4 d0 = *(const LAS f32x4*)(sh_s + row * 256 + 192 + quad * 8), d1 = *(const LAS f32x4*)(sh_s + row * 256 + 196 + quad * 8);
;                 const f32x4 e0 = *(const LAS f32x4*)(sh_s + row * 256 + 224 + quad * 8), e1 = *(const LAS f32x4*)(sh_s + row * 256 + 228 + quad * 8);
;                 u32x4 aw, aa;
;                 aw.x = cvt_pk_bf16(tanh_(d0[0]), tanh_(d0[1])); aw.y = cvt_pk_bf16(tanh_(d0[2]), tanh_(d0[3])); aw.z = cvt_pk_bf16(tanh_(d1[0]), tanh_(d1[1])); aw.w = cvt_pk_bf16(tanh_(d1[2]), tanh_(d1[3]));
;                 aa.x = cvt_pk_bf16(e0[0], e0[1]); aa.y = cvt_pk_bf16(e0[2], e0[3]); aa.z = cvt_pk_bf16(e1[0], e1[1]); aa.w = cvt_pk_bf16(e1[2], e1[3]);
;                 const bf16x8 bw = *(const LAS bf16x8*)(w2T + (ct * 16 + r16) * 40 + quad * 8), ba = *(const LAS bf16x8*)(a2T + (ct * 16 + r16) * 40 + quad * 8);
;                 const f32x4 z4 = {0.f, 0.f, 0.f, 0.f};
;                 const f32x4 cw = __builtin_amdgcn_mfma_f32_16x16x32_bf16(__builtin_bit_cast(bf16x8, aw), bw, z4, 0, 0, 0);
;                 const f32x4 ca = __builtin_amdgcn_mfma_f32_16x16x32_bf16(__builtin_bit_cast(bf16x8, aa), ba, z4, 0, 0, 0);
.Lrw_top:
	ds_read_b128 v[32:35], v206 offset:17664
	ds_read_b128 v[36:39], v206 offset:17680
	s_waitcnt vmcnt(1) lgkmcnt(0)
	v_lshlrev_b32_e32 v40, 16, v16
	v_and_b32_e32 v41, 0xffff0000, v16
	v_lshlrev_b32_e32 v42, 16, v24
	v_and_b32_e32 v43, 0xffff0000, v24
	v_lshlrev_b32_e32 v2, 16, v8
	v_and_b32_e32 v3, 0xffff0000, v8
	v_pk_add_f32 v[40:41], v[40:41], v[42:43]
	v_lshlrev_b32_e32 v42, 16, v26
	v_pk_fma_f32 v[40:41], v[40:41], 0.5, v[2:3] op_sel_hi:[1,0,1] neg_lo:[0,0,1] neg_hi:[0,0,1]
	v_and_b32_e32 v43, 0xffff0000, v26
	v_pk_fma_f32 v[32:33], v[40:41], v[32:33], v[2:3]
	v_lshlrev_b32_e32 v40, 16, v18
	v_and_b32_e32 v41, 0xffff0000, v18
	v_lshlrev_b32_e32 v2, 16, v10
	v_and_b32_e32 v3, 0xffff0000, v10
	v_pk_add_f32 v[40:41], v[40:41], v[42:43]
	v_lshlrev_b32_e32 v42, 16, v25
	v_pk_fma_f32 v[40:41], v[40:41], 0.5, v[2:3] op_sel_hi:[1,0,1] neg_lo:[0,0,1] neg_hi:[0,0,1]
	v_and_b32_e32 v43, 0xffff0000, v25
	v_pk_fma_f32 v[36:37], v[40:41], v[36:37], v[2:3]
	v_lshlrev_b32_e32 v40, 16, v17
	v_and_b32_e32 v41, 0xffff0000, v17
	v_lshlrev_b32_e32 v2, 16, v9
	v_and_b32_e32 v3, 0xffff0000, v9
	v_pk_add_f32 v[40:41], v[40:41], v[42:43]
	v_lshlrev_b32_e32 v42, 16, v27
	v_pk_fma_f32 v[40:41], v[40:41], 0.5, v[2:3] op_sel_hi:[1,0,1] neg_lo:[0,0,1] neg_hi:[0,0,1]
	v_and_b32_e32 v43, 0xffff0000, v27
	v_pk_fma_f32 v[34:35], v[40:41], v[34:35], v[2:3]
	v_lshlrev_b32_e32 v40, 16, v19
	v_and_b32_e32 v41, 0xffff0000, v19
	v_lshlrev_b32_e32 v2, 16, v11
	v_and_b32_e32 v3, 0xffff0000, v11
	v_pk_add_f32 v[40:41], v[40:41], v[42:43]
	v_lshlrev_b32_e32 v42, 16, v28
	v_pk_fma_f32 v[40:41], v[40:41], 0.5, v[2:3] op_sel_hi:[1,0,1] neg_lo:[0,0,1] neg_hi:[0,0,1]
	v_and_b32_e32 v43, 0xffff0000, v28
	v_pk_fma_f32 v[38:39], v[40:41], v[38:39], v[2:3]
	ds_write_b128 v87, v[32:35]
	ds_write_b128 v87, v[36:39] offset:16
	ds_read_b128 v[32:35], v206 offset:17696
	ds_read_b128 v[36:39], v206 offset:17712
	v_lshlrev_b32_e32 v40, 16, v20
	v_and_b32_e32 v41, 0xffff0000, v20
	v_lshlrev_b32_e32 v2, 16, v12
	v_and_b32_e32 v3, 0xffff0000, v12
	v_pk_add_f32 v[40:41], v[40:41], v[42:43]
	v_lshlrev_b32_e32 v42, 16, v30
	v_pk_fma_f32 v[40:41], v[40:41], 0.5, v[2:3] op_sel_hi:[1,0,1] neg_lo:[0,0,1] neg_hi:[0,0,1]
	v_and_b32_e32 v43, 0xffff0000, v30
	s_waitcnt lgkmcnt(1)
	v_pk_fma_f32 v[32:33], v[40:41], v[32:33], v[2:3]
	v_lshlrev_b32_e32 v40, 16, v22
	v_and_b32_e32 v41, 0xffff0000, v22
	v_lshlrev_b32_e32 v2, 16, v14
	v_and_b32_e32 v3, 0xffff0000, v14
	v_pk_add_f32 v[40:41], v[40:41], v[42:43]
	v_lshlrev_b32_e32 v42, 16, v29
	v_pk_fma_f32 v[40:41], v[40:41], 0.5, v[2:3] op_sel_hi:[1,0,1] neg_lo:[0,0,1] neg_hi:[0,0,1]
	v_and_b32_e32 v43, 0xffff0000, v29
	s_waitcnt lgkmcnt(0)
	v_pk_fma_f32 v[36:37], v[40:41], v[36:37], v[2:3]
	v_lshlrev_b32_e32 v40, 16, v21
	v_and_b32_e32 v41, 0xffff0000, v21
	v_lshlrev_b32_e32 v2, 16, v13
	v_and_b32_e32 v3, 0xffff0000, v13
	v_pk_add_f32 v[40:41], v[40:41], v[42:43]
	v_lshlrev_b32_e32 v42, 16, v31
	v_pk_fma_f32 v[40:41], v[40:41], 0.5, v[2:3] op_sel_hi:[1,0,1] neg_lo:[0,0,1] neg_hi:[0,0,1]
	v_and_b32_e32 v43, 0xffff0000, v31
	v_pk_fma_f32 v[34:35], v[40:41], v[34:35], v[2:3]
	v_lshlrev_b32_e32 v40, 16, v23
	v_and_b32_e32 v41, 0xffff0000, v23
	v_lshlrev_b32_e32 v2, 16, v15
	v_and_b32_e32 v3, 0xffff0000, v15
	v_pk_add_f32 v[40:41], v[40:41], v[42:43]
	s_add_i32 s62, s65, 1
	v_pk_fma_f32 v[40:41], v[40:41], 0.5, v[2:3] op_sel_hi:[1,0,1] neg_lo:[0,0,1] neg_hi:[0,0,1]
	s_nop 0
	v_pk_fma_f32 v[38:39], v[40:41], v[38:39], v[2:3]
	ds_write_b128 v87, v[32:35] offset:32
	ds_write_b128 v87, v[36:39] offset:48
	s_waitcnt lgkmcnt(0)
	s_barrier
	ds_read_b128 v[32:35], v89 offset:768
	ds_read_b128 v[36:39], v89 offset:784
	ds_read_b128 v[40:43], v89 offset:896
	s_waitcnt lgkmcnt(2)
	v_mul_f32_e64 v0, |v32|, -2.0
	v_mul_f32_e32 v0, 0x3fb8aa3b, v0
	v_exp_f32_e32 v2, v0
	v_mul_f32_e64 v0, |v33|, -2.0
	v_mul_f32_e32 v0, 0x3fb8aa3b, v0
	v_exp_f32_e32 v3, v0
	v_add_f32_e32 v0, 1.0, v2
	v_rcp_f32_e32 v44, v0
	v_cmp_gt_f32_e32 vcc, 0, v33
	v_add_f32_e32 v0, 1.0, v3
	v_rcp_f32_e32 v45, v0
	v_mul_f32_e64 v0, |v34|, -2.0
	v_pk_add_f32 v[2:3], v[2:3], 1.0 op_sel_hi:[1,0] neg_lo:[1,0] neg_hi:[1,0]
	v_mul_f32_e32 v0, 0x3fb8aa3b, v0
	v_pk_mul_f32 v[2:3], v[2:3], v[44:45]
	v_exp_f32_e32 v44, v0
	v_mul_f32_e64 v0, |v35|, -2.0
	v_mul_f32_e32 v0, 0x3fb8aa3b, v0
	v_exp_f32_e32 v45, v0
	v_cndmask_b32_e64 v0, v3, -v3, vcc
	v_add_f32_e32 v3, 1.0, v44
	v_cmp_gt_f32_e32 vcc, 0, v32
	v_rcp_f32_e32 v46, v3
	v_add_f32_e32 v3, 1.0, v45
	v_cndmask_b32_e64 v2, v2, -v2, vcc
	v_rcp_f32_e32 v47, v3
	v_cvt_pk_bf16_f32 v32, v2, v0
	s_waitcnt lgkmcnt(1)
	v_mul_f32_e64 v0, |v36|, -2.0
	v_mul_f32_e32 v0, 0x3fb8aa3b, v0
	v_pk_add_f32 v[2:3], v[44:45], 1.0 op_sel_hi:[1,0] neg_lo:[1,0] neg_hi:[1,0]
	v_exp_f32_e32 v44, v0
	v_mul_f32_e64 v0, |v37|, -2.0
	v_mul_f32_e32 v0, 0x3fb8aa3b, v0
	v_pk_mul_f32 v[2:3], v[2:3], v[46:47]
	v_exp_f32_e32 v45, v0
	v_cmp_gt_f32_e32 vcc, 0, v35
	s_waitcnt lgkmcnt(0)
	v_cvt_pk_bf16_f32 v40, v40, v41
	v_cvt_pk_bf16_f32 v41, v42, v43
	v_cndmask_b32_e64 v0, v3, -v3, vcc
	v_cmp_gt_f32_e32 vcc, 0, v34
	v_add_f32_e32 v3, 1.0, v44
	v_rcp_f32_e32 v46, v3
	v_cndmask_b32_e64 v2, v2, -v2, vcc
	v_cvt_pk_bf16_f32 v33, v2, v0
	v_mul_f32_e64 v0, |v38|, -2.0
	v_add_f32_e32 v3, 1.0, v45
	v_mul_f32_e32 v0, 0x3fb8aa3b, v0
	v_rcp_f32_e32 v47, v3
	v_pk_add_f32 v[2:3], v[44:45], 1.0 op_sel_hi:[1,0] neg_lo:[1,0] neg_hi:[1,0]
	v_exp_f32_e32 v44, v0
	v_mul_f32_e64 v0, |v39|, -2.0
	v_mul_f32_e32 v0, 0x3fb8aa3b, v0
	v_exp_f32_e32 v45, v0
	v_pk_mul_f32 v[2:3], v[2:3], v[46:47]
	v_cmp_gt_f32_e32 vcc, 0, v37
	s_nop 1
	v_cndmask_b32_e64 v0, v3, -v3, vcc
	v_add_f32_e32 v3, 1.0, v44
	v_rcp_f32_e32 v46, v3
	v_add_f32_e32 v3, 1.0, v45
	v_rcp_f32_e32 v47, v3
	v_cmp_gt_f32_e32 vcc, 0, v36
	s_nop 1
	v_cndmask_b32_e64 v2, v2, -v2, vcc
	v_cvt_pk_bf16_f32 v34, v2, v0
	v_pk_add_f32 v[2:3], v[44:45], 1.0 op_sel_hi:[1,0] neg_lo:[1,0] neg_hi:[1,0]
	v_cmp_gt_f32_e32 vcc, 0, v39
	v_pk_mul_f32 v[2:3], v[2:3], v[46:47]
	s_nop 0
	v_cndmask_b32_e64 v0, v3, -v3, vcc
	v_cmp_gt_f32_e32 vcc, 0, v38
	ds_read_b128 v[36:39], v91
	ds_read_b128 v[44:47], v89 offset:912
	v_cndmask_b32_e64 v2, v2, -v2, vcc
	v_cvt_pk_bf16_f32 v35, v2, v0
	ds_read_b128 v[58:61], v91 offset:5120
	ds_read2st64_b32 v[2:3], v207 offset0:64 offset1:65
	s_waitcnt lgkmcnt(3)
; #define LAS __attribute__((address_space(3)))
; __device__ __forceinline__ float bf_lo(unsigned w) { return __uint_as_float(w << 16); }
; __device__ void rwkv_chunk_phase(const Params& p, int l, LAS unsigned char* lds) {
;     ...
;                 const f32x4 cw = __builtin_amdgcn_mfma_f32_16x16x32_bf16(__builtin_bit_cast(bf16x8, aw), bw, z4, 0, 0, 0);
;                 const f32x4 ca = __builtin_amdgcn_mfma_f32_16x16x32_bf16(__builtin_bit_cast(bf16x8, aa), ba, z4, 0, 0, 0);
;                 const int col = ct * 16 + r16; const float w0c = c_s[col], a0c = c_s[64 + col];
;                 f32x4 lwv, lo;
; #pragma unroll
;                 for (int j = 0; j < 4; ++j) { const int tr_ = rt * 16 + quad * 4 + j; lwv[j] = -__expf(-softplus_(-(cw[j] + w0c)) - 0.5f); y_s[tr_ * 64 + col] = lwv[j]; lg_s[tr_ * 64 + col] = ca[j] + a0c; }
;                 const unsigned h01 = cvt_pk_bf16(lwv[0], lwv[1]), h23 = cvt_pk_bf16(lwv[2], lwv[3]);
;                 lo[0] = lwv[0] - bf_lo(h01); lo[1] = lwv[1] - bf_hi(h01); lo[2] = lwv[2] - bf_lo(h23); lo[3] = lwv[3] - bf_hi(h23);
;                 u32x2 hw; hw.x = h01; hw.y = h23; *(LAS u32x2*)(lwT_hi + col * 40 + rt * 16 + quad * 4) = hw; st_bf4(lwT_lo + col * 40 + rt * 16 + quad * 4, lo); }
;             LBAR();
;             {   const f32x4 wp = *(const LAS f32x4*)(y_s + tok * 64 + j0), ap = *(const LAS f32x4*)(lg_s + tok * 64 + j0);
;                 r4 = *(const LAS f32x4*)(sh_s + tok * 256 + j0); const f32x4 kv4 = *(const LAS f32x4*)(sh_s + tok * 256 + 64 + j0); v4 = *(const LAS f32x4*)(sh_s + tok * 256 + 128 + j0);
;                 float ss = 0.f, bs = 0.f;
; #pragma unroll
;                 for (int j = 0; j < 4; ++j) { kk4[j] = kv4[j] * c_s[128 + j0 + j]; ss += kk4[j] * kk4[j]; }
;                 ss = red16d(ss);
;                 const float rn_ = rsqrtf(ss + 1e-12f);
; #pragma unroll
;                 for (int j = 0; j < 4; ++j) {
;                     const float a = sigmoid_(ap[j]);
;                     lw4[j] = wp[j];
;                     kk4[j] *= rn_; b4[j] = kk4[j] * a;
;                     kd4[j] = kv4[j] * (1.0f + (a - 1.0f) * c_s[192 + j0 + j]);
;                     bs += r4[j] * kd4[j] * c_s[256 + j0 + j];
;                 }
;                 bs = red16d(bs);
;                 if (dir == 0 && cg == 0) BON[(t0 + tokm) * 8 + h] = bs;
	v_mfma_f32_16x16x32_bf16 v[32:35], v[32:35], v[36:39], 0
	s_waitcnt lgkmcnt(2)
	v_cvt_pk_bf16_f32 v42, v44, v45
	v_cvt_pk_bf16_f32 v43, v46, v47
	s_waitcnt lgkmcnt(0)
	s_nop 3
	v_add_f32_e32 v0, v32, v2
	v_mul_f32_e64 v32, |v0|, s97
	v_exp_f32_e32 v32, v32
	v_add_f32_e32 v33, v33, v2
	v_max_f32_e64 v0, -v0, 0
	v_add_f32_e32 v34, v34, v2
	v_add_f32_e32 v32, 1.0, v32
	v_cmp_gt_f32_e64 s[24:25], s33, v32
	v_add_f32_e32 v2, v35, v2
	v_mul_f32_e64 v35, |v2|, s97
	v_cndmask_b32_e64 v36, 0, 32, s[24:25]
	v_ldexp_f32 v32, v32, v36
	v_log_f32_e32 v32, v32
	v_mfma_f32_16x16x32_bf16 v[36:39], v[40:43], v[58:61], 0
	v_exp_f32_e32 v35, v35
	v_max_f32_e64 v2, -v2, 0
	v_mul_f32_e32 v40, 0x3f317217, v32
	v_fma_f32 v40, v32, s48, -v40
	v_fmac_f32_e32 v40, 0x3377d1cf, v32
	v_fmac_f32_e32 v40, 0x3f317217, v32
	v_cmp_lt_f32_e64 vcc, |v32|, s49
	v_add_f32_e32 v35, 1.0, v35
	v_add_f32_e32 v37, v37, v3
	v_cndmask_b32_e32 v32, v32, v40, vcc
	v_cndmask_b32_e64 v40, 0, v176, s[24:25]
	v_sub_f32_e32 v32, v32, v40
	v_mul_f32_e64 v40, |v33|, s97
	v_exp_f32_e32 v40, v40
	v_add_f32_e32 v0, v0, v32
	v_sub_f32_e32 v0, -0.5, v0
	v_mul_f32_e32 v0, 0x3fb8aa3b, v0
	v_add_f32_e32 v32, 1.0, v40
	v_cmp_gt_f32_e32 vcc, s33, v32
	v_max_f32_e64 v33, -v33, 0
	v_add_f32_e32 v38, v38, v3
	v_cndmask_b32_e64 v40, 0, 32, vcc
	v_ldexp_f32 v32, v32, v40
	v_log_f32_e32 v40, v32
	v_exp_f32_e32 v32, v0
	v_add_f32_e32 v0, v36, v3
	v_add_f32_e32 v39, v39, v3
	v_mul_f32_e32 v36, 0x3f317217, v40
	v_fma_f32 v36, v40, s48, -v36
	v_fmac_f32_e32 v36, 0x3377d1cf, v40
	v_fmac_f32_e32 v36, 0x3f317217, v40
	v_cmp_lt_f32_e64 s[24:25], |v40|, s49
	s_nop 1
	v_cndmask_b32_e64 v36, v40, v36, s[24:25]
	v_cndmask_b32_e32 v40, 0, v176, vcc
	v_sub_f32_e32 v36, v36, v40
	v_mul_f32_e64 v40, |v34|, s97
	v_exp_f32_e32 v40, v40
	v_add_f32_e32 v33, v33, v36
	v_max_f32_e64 v34, -v34, 0
	v_sub_f32_e32 v33, -0.5, v33
	v_add_f32_e32 v36, 1.0, v40
	v_cmp_gt_f32_e32 vcc, s33, v36
	v_mul_f32_e32 v33, 0x3fb8aa3b, v33
	v_exp_f32_e32 v33, v33
	v_cndmask_b32_e64 v40, 0, 32, vcc
	v_ldexp_f32 v36, v36, v40
	v_log_f32_e32 v36, v36
	s_nop 0
	v_mul_f32_e32 v40, 0x3f317217, v36
	v_fma_f32 v40, v36, s48, -v40
	v_fmac_f32_e32 v40, 0x3377d1cf, v36
	v_fmac_f32_e32 v40, 0x3f317217, v36
	v_cmp_lt_f32_e64 s[24:25], |v36|, s49
	s_nop 1
	v_cndmask_b32_e64 v36, v36, v40, s[24:25]
	v_cndmask_b32_e32 v40, 0, v176, vcc
	v_sub_f32_e32 v36, v36, v40
	v_cmp_gt_f32_e32 vcc, s33, v35
	v_add_f32_e32 v34, v34, v36
	v_sub_f32_e32 v34, -0.5, v34
	v_cndmask_b32_e64 v36, 0, 32, vcc
	v_ldexp_f32 v35, v35, v36
	v_log_f32_e32 v35, v35
	v_mul_f32_e32 v34, 0x3fb8aa3b, v34
	v_exp_f32_e32 v34, v34
	v_xor_b32_e32 v40, 0x80000000, v32
	v_mul_f32_e32 v36, 0x3f317217, v35
	v_fma_f32 v36, v35, s48, -v36
	v_fmac_f32_e32 v36, 0x3377d1cf, v35
	v_fmac_f32_e32 v36, 0x3f317217, v35
	v_cmp_lt_f32_e64 s[24:25], |v35|, s49
	s_nop 1
	v_cndmask_b32_e64 v35, v35, v36, s[24:25]
	v_cndmask_b32_e32 v36, 0, v176, vcc
	v_sub_f32_e32 v35, v35, v36
	v_add_f32_e32 v2, v2, v35
	v_sub_f32_e32 v2, -0.5, v2
	v_mul_f32_e32 v2, 0x3fb8aa3b, v2
	v_exp_f32_e32 v35, v2
	v_pk_add_f32 v[2:3], v[32:33], 0 neg_lo:[1,1] neg_hi:[1,1]
	v_xor_b32_e32 v36, 0x80000000, v33
	v_cvt_pk_bf16_f32 v2, v2, v3
	ds_write2st64_b32 v148, v0, v40 offset0:82 offset1:114
	ds_write2st64_b32 v150, v37, v36 offset0:82 offset1:114
	v_lshlrev_b32_e32 v36, 16, v2
	v_and_b32_e32 v37, 0xffff0000, v2
	v_pk_add_f32 v[32:33], v[32:33], v[36:37] neg_lo:[1,1] neg_hi:[1,1]
	v_pk_add_f32 v[36:37], v[34:35], 0 neg_lo:[1,1] neg_hi:[1,1]
	v_xor_b32_e32 v3, 0x80000000, v34
	v_xor_b32_e32 v0, 0x80000000, v35
	ds_write2st64_b32 v152, v38, v3 offset0:82 offset1:114
	ds_write2st64_b32 v154, v39, v0 offset0:82 offset1:114
	v_cvt_pk_bf16_f32 v3, v36, v37
	v_lshlrev_b32_e32 v36, 16, v3
	v_and_b32_e32 v37, 0xffff0000, v3
	v_pk_add_f32 v[34:35], v[34:35], v[36:37] neg_lo:[1,1] neg_hi:[1,1]
	ds_write_b64 v92, v[2:3]
	v_cvt_pk_bf16_f32 v2, v32, v33
	v_cvt_pk_bf16_f32 v3, v34, v35
	ds_write_b64 v93, v[2:3]
	s_waitcnt lgkmcnt(0)
	s_barrier
	ds_read_b128 v[36:39], v94 offset:29184
	ds_read_b128 v[32:35], v94 offset:20992
	ds_read_b128 v[44:47], v96 offset:17408
	ds_read_b128 v[218:221], v96 offset:17152
	ds_read_b128 v[40:43], v95
	ds_read_b128 v[222:225], v95 offset:256
	s_and_b64 s[24:25], s[4:5], exec
	s_cselect_b32 s24, s62, s63
	s_lshl_b32 s24, s24, 5
	s_waitcnt lgkmcnt(4)
	v_mul_f32_e32 v0, 0xbfb8aa3b, v32
	v_exp_f32_e32 v0, v0
	v_mul_f32_e32 v2, 0xbfb8aa3b, v33
	v_exp_f32_e32 v2, v2
	s_or_b32 s24, s60, s24
	v_add_f32_e32 v0, 1.0, v0
	v_rcp_f32_e32 v64, v0
	v_add_f32_e32 v0, 1.0, v2
	v_rcp_f32_e32 v65, v0
	s_mov_b32 s25, s61
	v_lshl_add_u64 v[58:59], s[24:25], 0, v[52:53]
	v_pk_add_f32 v[2:3], v[64:65], -1.0 op_sel_hi:[1,0]
	s_waitcnt lgkmcnt(2)
	v_pk_fma_f32 v[2:3], v[2:3], v[218:219], 1.0 op_sel_hi:[1,1,0]
	s_waitcnt lgkmcnt(0)
	v_pk_mul_f32 v[62:63], v[222:223], v[2:3]
	v_mul_f32_e32 v3, 0xbfb8aa3b, v35
	v_mul_f32_e32 v0, v40, v62
	v_fma_f32 v0, v44, v0, 0
	v_mul_f32_e32 v2, v41, v63
	v_fmac_f32_e32 v0, v45, v2
	v_mul_f32_e32 v2, 0xbfb8aa3b, v34
	ds_read_b128 v[32:35], v95 offset:512
	ds_read_b128 v[226:229], v96 offset:16896
	v_exp_f32_e32 v2, v2
	v_exp_f32_e32 v3, v3
	v_add_f32_e32 v2, 1.0, v2
	s_waitcnt lgkmcnt(0)
	v_pk_mul_f32 v[70:71], v[222:223], v[226:227]
	v_rcp_f32_e32 v66, v2
	v_add_f32_e32 v2, 1.0, v3
	v_pk_mul_f32 v[68:69], v[224:225], v[228:229]
	v_pk_mul_f32 v[44:45], v[70:71], v[70:71]
	v_rcp_f32_e32 v67, v2
	v_pk_mul_f32 v[2:3], v[68:69], v[68:69]
	v_add_f32_e32 v44, v44, v45
	v_add_f32_e32 v2, v44, v2
	v_add_f32_e32 v2, v2, v3
	s_nop 1
	v_add_f32_dpp v2, v2, v2 quad_perm:[1,0,3,2] row_mask:0xf bank_mask:0xf bound_ctrl:1
	s_nop 1
	v_add_f32_dpp v2, v2, v2 quad_perm:[2,3,0,1] row_mask:0xf bank_mask:0xf bound_ctrl:1
	s_nop 1
	v_add_f32_dpp v51, v2, v2 row_half_mirror row_mask:0xf bank_mask:0xf bound_ctrl:1
	v_pk_add_f32 v[2:3], v[66:67], -1.0 op_sel_hi:[1,0]
	s_nop 0
	v_pk_fma_f32 v[2:3], v[2:3], v[220:221], 1.0 op_sel_hi:[1,1,0]
	v_mov_b32_dpp v218, v51 row_mirror row_mask:0xf bank_mask:0xf bound_ctrl:1
	v_pk_mul_f32 v[60:61], v[224:225], v[2:3]
	s_nop 0
	v_mul_f32_e32 v2, v42, v60
	v_fmac_f32_e32 v0, v46, v2
	v_mul_f32_e32 v2, v43, v61
	v_fmac_f32_e32 v0, v47, v2
	s_nop 1
	v_add_f32_dpp v0, v0, v0 quad_perm:[1,0,3,2] row_mask:0xf bank_mask:0xf bound_ctrl:1
	s_nop 1
	v_add_f32_dpp v0, v0, v0 quad_perm:[2,3,0,1] row_mask:0xf bank_mask:0xf bound_ctrl:1
	s_nop 1
	v_add_f32_dpp v0, v0, v0 row_half_mirror row_mask:0xf bank_mask:0xf bound_ctrl:1
	s_nop 1
	v_mov_b32_dpp v2, v0 row_mirror row_mask:0xf bank_mask:0xf bound_ctrl:1
	s_and_saveexec_b64 s[24:25], s[6:7]
	s_cbranch_execz .LBB0_323
	v_add_f32_e32 v0, v0, v2
	v_lshlrev_b64 v[2:3], 5, v[58:59]
	v_lshl_add_u64 v[2:3], s[40:41], 0, v[2:3]
	global_store_dword v[2:3], v0, off

; #define LAS __attribute__((address_space(3)))
; __device__ __forceinline__ uint4 pack8(const float (&f)[8]) { uint4 r; r.x = cvt_pk_bf16(f[0], f[1]); r.y = cvt_pk_bf16(f[2], f[3]); r.z = cvt_pk_bf16(f[4], f[5]); r.w = cvt_pk_bf16(f[6], f[7]); return r; }
; #define LBAR() do { asm volatile("s_waitcnt lgkmcnt(0)" ::: "memory"); __builtin_amdgcn_s_barrier(); asm volatile("" ::: "memory"); } while (0)
; __device__ void gla_chunk_phase(const Params& p, int l, LAS unsigned char* lds) {
;     ...
;             {   const f32x4 b0 = *(const LAS f32x4*)(b_s + ltok * 64 + lc8), b1 = *(const LAS f32x4*)(b_s + ltok * 64 + lc8 + 4);
;                 const f32x4 d0 = *(const LAS f32x4*)(dk_s + lc8), d1 = *(const LAS f32x4*)(dk_s + lc8 + 4);
;                 float qv[8], kv[8], ktv[8];
; #pragma unroll
;                 for (int j = 0; j < 8; ++j) {
;                     const float bb = (j < 4) ? b0[j & 3] : b1[j & 3], dkj = (j < 4) ? d0[j & 3] : d1[j & 3];
;                     const float e = __expf(bb), einv = __builtin_amdgcn_rcpf(e);
;                     qv[j] = fq[j] * 0.125f * e; kv[j] = fk[j] * einv;
;                     ktv[j] = kv[j] * dkj;
;                 }
;                 const uint4 q4 = pack8(qv), k4 = pack8(kv), t4 = pack8(ktv), v4 = pack8(fv);
;                 *(LAS u32x4*)(qd + ltok * 72 + lc8) = (u32x4){q4.x, q4.y, q4.z, q4.w}; *(LAS u32x4*)(kd + ltok * 72 + lc8) = (u32x4){k4.x, k4.y, k4.z, k4.w};
;                 *(LAS u32x4*)(ktT + ltok * 72 + lc8) = (u32x4){t4.x, t4.y, t4.z, t4.w}; *(LAS u32x4*)(vT + ltok * 72 + lc8) = (u32x4){v4.x, v4.y, v4.z, v4.w}; }
;             LBAR();
.LBB0_435:
	s_or_b64 exec, exec, s[20:21]
	s_waitcnt lgkmcnt(0)
	s_barrier
	s_waitcnt vmcnt(0)
	s_nop 0
	v_lshlrev_b32_e32 v44, 16, v38
	v_and_b32_e32 v45, 0xffff0000, v38
	v_lshlrev_b32_e32 v62, 16, v39
	v_and_b32_e32 v63, 0xffff0000, v39
	v_lshlrev_b32_e32 v120, 16, v40
	v_and_b32_e32 v121, 0xffff0000, v40
	v_lshlrev_b32_e32 v122, 16, v41
	v_and_b32_e32 v123, 0xffff0000, v41
	v_lshlrev_b32_e32 v124, 16, v30
	v_and_b32_e32 v125, 0xffff0000, v30
	v_lshlrev_b32_e32 v126, 16, v31
	v_and_b32_e32 v127, 0xffff0000, v31
	v_lshlrev_b32_e32 v128, 16, v32
	v_and_b32_e32 v129, 0xffff0000, v32
	v_lshlrev_b32_e32 v30, 16, v33
	v_and_b32_e32 v31, 0xffff0000, v33
	v_lshlrev_b32_e32 v53, 16, v34
	v_and_b32_e32 v115, 0xffff0000, v34
	v_lshlrev_b32_e32 v148, 16, v35
	v_and_b32_e32 v149, 0xffff0000, v35
	v_lshlrev_b32_e32 v150, 16, v36
	v_and_b32_e32 v151, 0xffff0000, v36
	v_lshlrev_b32_e32 v152, 16, v37
	v_and_b32_e32 v153, 0xffff0000, v37
	ds_read_b128 v[32:35], v76
	ds_read_b128 v[36:39], v76 offset:16
	ds_read_b128 v[40:43], v77
	ds_read_b128 v[116:119], v77 offset:16
	v_pk_mul_f32 v[44:45], v[44:45], s[74:75] op_sel_hi:[1,0]
	s_waitcnt lgkmcnt(3)
	v_mul_f32_e32 v32, 0x3fb8aa3b, v32
	v_mul_f32_e32 v33, 0x3fb8aa3b, v33
	v_exp_f32_e32 v32, v32
	v_exp_f32_e32 v33, v33
	v_mul_f32_e32 v34, 0x3fb8aa3b, v34
	v_mul_f32_e32 v35, 0x3fb8aa3b, v35
	v_rcp_f32_e32 v138, v32
	v_rcp_f32_e32 v139, v33
	v_exp_f32_e32 v34, v34
	v_exp_f32_e32 v35, v35
	s_waitcnt lgkmcnt(2)
	v_mul_f32_e32 v36, 0x3fb8aa3b, v36
	v_mul_f32_e32 v37, 0x3fb8aa3b, v37
	v_pk_mul_f32 v[32:33], v[44:45], v[32:33]
	v_pk_mul_f32 v[44:45], v[138:139], v[124:125]
	v_rcp_f32_e32 v124, v34
	v_rcp_f32_e32 v125, v35
	v_exp_f32_e32 v36, v36
	v_exp_f32_e32 v37, v37
	v_pk_mul_f32 v[62:63], v[62:63], s[74:75] op_sel_hi:[1,0]
	v_mul_f32_e32 v38, 0x3fb8aa3b, v38
	v_mul_f32_e32 v39, 0x3fb8aa3b, v39
	v_pk_mul_f32 v[34:35], v[62:63], v[34:35]
	v_pk_mul_f32 v[62:63], v[124:125], v[126:127]
	v_rcp_f32_e32 v124, v36
	v_rcp_f32_e32 v125, v37
	v_exp_f32_e32 v38, v38
	v_exp_f32_e32 v39, v39
	v_pk_mul_f32 v[120:121], v[120:121], s[74:75] op_sel_hi:[1,0]
	v_pk_mul_f32 v[122:123], v[122:123], s[74:75] op_sel_hi:[1,0]
	v_pk_mul_f32 v[36:37], v[120:121], v[36:37]
	v_pk_mul_f32 v[120:121], v[124:125], v[128:129]
	v_rcp_f32_e32 v124, v38
	v_rcp_f32_e32 v125, v39
	v_pk_mul_f32 v[38:39], v[122:123], v[38:39]
	s_waitcnt lgkmcnt(1)
	v_pk_mul_f32 v[40:41], v[40:41], v[44:45]
	v_pk_mul_f32 v[42:43], v[42:43], v[62:63]
	v_pk_mul_f32 v[122:123], v[124:125], v[30:31]
	s_waitcnt lgkmcnt(0)
	v_pk_mul_f32 v[116:117], v[116:117], v[120:121]
	v_pk_mul_f32 v[118:119], v[118:119], v[122:123]
	v_cvt_pk_bf16_f32 v30, v32, v33
	v_cvt_pk_bf16_f32 v31, v34, v35
	v_cvt_pk_bf16_f32 v32, v36, v37
	v_cvt_pk_bf16_f32 v33, v38, v39
	v_cvt_pk_bf16_f32 v34, v44, v45
	v_cvt_pk_bf16_f32 v35, v62, v63
	v_cvt_pk_bf16_f32 v36, v120, v121
	v_cvt_pk_bf16_f32 v37, v122, v123
	v_cvt_pk_bf16_f32 v38, v40, v41
	v_cvt_pk_bf16_f32 v39, v42, v43
	v_cvt_pk_bf16_f32 v40, v116, v117
	v_cvt_pk_bf16_f32 v41, v118, v119
	v_cvt_pk_bf16_f32 v42, v53, v115
	v_cvt_pk_bf16_f32 v43, v148, v149
	v_cvt_pk_bf16_f32 v44, v150, v151
	v_cvt_pk_bf16_f32 v45, v152, v153
	ds_write_b128 v50, v[30:33] offset:16384
	ds_write_b128 v50, v[34:37] offset:25600
	ds_write_b128 v50, v[38:41] offset:34816
	ds_write_b128 v50, v[42:45] offset:44032
	s_waitcnt lgkmcnt(0)
	s_barrier
; __device__ void gla_chunk_phase(const Params& p, int l, LAS unsigned char* lds) {
;     ...
;             f32x4 oacc[2] = {{0.f, 0.f, 0.f, 0.f}, {0.f, 0.f, 0.f, 0.f}};
;             {
;                 f32x4 sc[2] = {{0.f, 0.f, 0.f, 0.f}, {0.f, 0.f, 0.f, 0.f}};
;                 const f32x4 dkv = *(const LAS f32x4*)(dk_s + tr * 16 + quad * 4);
;                 sacc[0] *= dkv; sacc[1] *= dkv;
;                 const int arow = (tr * 16 + r16) * 72 + quad * 8;
; #pragma unroll
;                 for (int ks = 0; ks < 2; ++ks) {
;                     const bf16x8 a_kd = *(const LAS bf16x8*)(kd + arow + ks * 32), a_st = *(const LAS bf16x8*)(stT + arow + ks * 32), a_kt = trfrag(ktT, 72, ks * 32, tr * 16, lane);
; #pragma unroll
;                     for (int t = 0; t < 2; ++t) { const int brow = ((tcb + t) * 16 + r16) * 72 + ks * 32 + quad * 8;
;                         const bf16x8 b_qd = *(const LAS bf16x8*)(qd + brow), b_vT = trfrag(vT, 72, ks * 32, (tcb + t) * 16, lane);
;                         sc[t] = __builtin_amdgcn_mfma_f32_16x16x32_bf16(a_kd, b_qd, sc[t], 0, 0, 0);
;                         oacc[t] = __builtin_amdgcn_mfma_f32_16x16x32_bf16(a_st, b_qd, oacc[t], 0, 0, 0);
;                         sacc[t] = __builtin_amdgcn_mfma_f32_16x16x32_bf16(a_kt, b_vT, sacc[t], 0, 0, 0); } }
; #pragma unroll
;                 for (int t = 0; t < 2; ++t) { const int lrow = (tcb + t) * 16 + r16; float pv[4];
; #pragma unroll
;                     for (int j = 0; j < 4; ++j) { const int m = tr * 16 + quad * 4 + j; const bool keep = dir ? (lrow > m) : (lrow >= m); pv[j] = keep ? sc[t][j] : 0.f; }
;                     u32x2 pw; pw.x = cvt_pk_bf16(pv[0], pv[1]); pw.y = cvt_pk_bf16(pv[2], pv[3]);
;                     *(LAS u32x2*)(Pm + lrow * 72 + tr * 16 + quad * 4) = pw; } }
;             LBAR();
;             {
;                 const int arow = (tr * 16 + r16) * 72 + quad * 8;
; #pragma unroll
;                 for (int ks = 0; ks < 2; ++ks) { const bf16x8 a_v = trfrag(vT, 72, ks * 32, tr * 16, lane);
; #pragma unroll
;                     for (int t = 0; t < 2; ++t) { const bf16x8 b_P = *(const LAS bf16x8*)(Pm + ((tcb + t) * 16 + r16) * 72 + ks * 32 + quad * 8);
;                         oacc[t] = __builtin_amdgcn_mfma_f32_16x16x32_bf16(a_v, b_P, oacc[t], 0, 0, 0); } }
; #pragma unroll
;                 for (int t = 0; t < 2; ++t) { const int cr = (tcb + t) * 16 + r16;
	ds_read_b128 v[30:33], v51
	v_add_u32_e32 v53, v79, v87
	v_add_u32_e32 v62, v81, v87
	v_add_u32_e32 v63, v81, v95
	v_add_u32_e32 v115, v79, v95
	s_waitcnt lgkmcnt(0)
	v_pk_mul_f32 v[24:25], v[24:25], v[32:33]
	v_pk_mul_f32 v[22:23], v[22:23], v[30:31]
	v_pk_mul_f32 v[28:29], v[28:29], v[32:33]
	v_pk_mul_f32 v[26:27], v[26:27], v[30:31]
	ds_read_b128 v[30:33], v78 offset:25600
	ds_read_b128 v[34:37], v78 offset:62464
	ds_read_b64_tr_b16 v[38:39], v88 offset:34816
	ds_read_b64_tr_b16 v[40:41], v88 offset:35392
	ds_read_b128 v[42:45], v53 offset:16384
	ds_read_b64_tr_b16 v[116:117], v89 offset:44032
	ds_read_b64_tr_b16 v[118:119], v89 offset:44608
	s_waitcnt lgkmcnt(0)
	v_mfma_f32_16x16x32_bf16 v[22:25], v[38:41], v[116:119], v[22:25]
	ds_read_b128 v[116:119], v110 offset:16384
	ds_read_b64_tr_b16 v[124:125], v90 offset:44032
	ds_read_b64_tr_b16 v[126:127], v90 offset:44608
	s_add_i32 s22, s41, -1
	s_add_i32 s23, s42, 1
	v_mfma_f32_16x16x32_bf16 v[120:123], v[30:33], v[42:45], 0
	s_and_b64 s[20:21], exec, s[76:77]
	s_cselect_b32 s20, s22, s23
	s_lshl_b32 s86, s20, 6
	v_mfma_f32_16x16x32_bf16 v[42:45], v[34:37], v[42:45], 0
	s_add_i32 s42, s42, -1
	s_add_i32 s41, s41, 1
	s_cmp_eq_u32 s42, -2
	s_waitcnt lgkmcnt(2)
	v_mfma_f32_16x16x32_bf16 v[30:33], v[30:33], v[116:119], 0
	v_mfma_f32_16x16x32_bf16 v[34:37], v[34:37], v[116:119], 0
	s_waitcnt lgkmcnt(0)
	v_mfma_f32_16x16x32_bf16 v[26:29], v[38:41], v[124:127], v[26:29]
	ds_read_b128 v[38:41], v78 offset:25664
	ds_read_b128 v[116:119], v78 offset:62528
	ds_read_b64_tr_b16 v[124:125], v91 offset:34816
	ds_read_b64_tr_b16 v[126:127], v91 offset:35392
	ds_read_b128 v[148:151], v53 offset:16448
	ds_read_b64_tr_b16 v[152:153], v92 offset:44032
	ds_read_b64_tr_b16 v[154:155], v92 offset:44608
	s_waitcnt lgkmcnt(2)
	v_mfma_f32_16x16x32_bf16 v[120:123], v[38:41], v[148:151], v[120:123]
	v_mfma_f32_16x16x32_bf16 v[42:45], v[116:119], v[148:151], v[42:45]
	s_waitcnt lgkmcnt(0)
	v_mfma_f32_16x16x32_bf16 v[22:25], v[124:127], v[152:155], v[22:25]
	ds_read_b128 v[148:151], v110 offset:16448
	ds_read_b64_tr_b16 v[152:153], v93 offset:44032
	ds_read_b64_tr_b16 v[154:155], v93 offset:44608
	s_waitcnt lgkmcnt(2)
	v_mfma_f32_16x16x32_bf16 v[30:33], v[38:41], v[148:151], v[30:33]
	v_cndmask_b32_e32 v38, 0, v120, vcc
	v_cndmask_b32_e64 v39, 0, v121, s[6:7]
	v_cndmask_b32_e64 v40, 0, v122, s[8:9]
	v_cndmask_b32_e64 v41, 0, v123, s[10:11]
	v_cvt_pk_bf16_f32 v38, v38, v39
	s_nop 2
	v_cndmask_b32_e64 v30, 0, v30, s[12:13]
	v_cndmask_b32_e64 v31, 0, v31, s[14:15]
	v_cndmask_b32_e64 v32, 0, v32, s[16:17]
	v_cndmask_b32_e64 v33, 0, v33, s[18:19]
	v_cvt_pk_bf16_f32 v39, v40, v41
	v_cvt_pk_bf16_f32 v30, v30, v31
	v_cvt_pk_bf16_f32 v31, v32, v33
	ds_write_b64 v62, v[38:39] offset:53248
	ds_write_b64 v63, v[30:31] offset:53248
	s_waitcnt lgkmcnt(0)
	s_barrier
	ds_read_b64_tr_b16 v[30:31], v111 offset:44032
	ds_read_b64_tr_b16 v[32:33], v111 offset:44608
	ds_read_b128 v[38:41], v53 offset:53248
	s_waitcnt lgkmcnt(0)
	v_mfma_f32_16x16x32_bf16 v[38:41], v[30:33], v[38:41], v[42:45]
	s_nop 2
	ds_read_b128 v[42:45], v115 offset:53248
	v_mfma_f32_16x16x32_bf16 v[34:37], v[116:119], v[148:151], v[34:37]
	s_waitcnt lgkmcnt(0)
	v_mfma_f32_16x16x32_bf16 v[30:33], v[30:33], v[42:45], v[34:37]
	s_nop 5
	ds_read_b64_tr_b16 v[34:35], v111 offset:48640
	ds_read_b64_tr_b16 v[36:37], v111 offset:49216
	ds_read_b128 v[42:45], v53 offset:53312
	s_waitcnt lgkmcnt(0)
	v_mfma_f32_16x16x32_bf16 v[38:41], v[34:37], v[42:45], v[38:41]
	ds_read_b128 v[42:45], v115 offset:53312
	v_mfma_f32_16x16x32_bf16 v[26:29], v[124:127], v[152:155], v[26:29]
	s_nop 5
	ds_write_b128 v112, v[38:41]
	v_mov_b64_e32 v[38:39], v[10:11]
	v_mov_b64_e32 v[40:41], v[12:13]
	s_waitcnt lgkmcnt(1)
	v_mfma_f32_16x16x32_bf16 v[30:33], v[34:37], v[42:45], v[30:33]
	v_cvt_pk_bf16_f32 v34, v22, v23
	v_cvt_pk_bf16_f32 v35, v24, v25
	ds_write_b64 v62, v[34:35] offset:62464
	s_nop 4
	ds_write_b128 v113, v[30:33]
	v_cvt_pk_bf16_f32 v30, v26, v27
	v_cvt_pk_bf16_f32 v31, v28, v29
	ds_write_b64 v63, v[30:31] offset:62464
	s_waitcnt lgkmcnt(0)
	s_barrier
	ds_read_b128 v[30:33], v82
	ds_read_b128 v[34:37], v82 offset:16
	s_waitcnt lgkmcnt(1)
	v_cvt_pk_bf16_f32 v30, v30, v31
	v_cvt_pk_bf16_f32 v31, v32, v33
	s_waitcnt lgkmcnt(0)
	v_cvt_pk_bf16_f32 v32, v34, v35
	v_lshl_add_u64 v[34:35], v[60:61], 0, s[86:87]
	v_lshlrev_b64 v[34:35], 10, v[34:35]
	v_cvt_pk_bf16_f32 v33, v36, v37
	v_lshl_add_u64 v[34:35], v[56:57], 0, v[34:35]
	global_store_dwordx4 v[34:35], v[30:33], off
	v_mov_b64_e32 v[34:35], v[18:19]
	v_mov_b64_e32 v[36:37], v[20:21]
	v_mov_b64_e32 v[30:31], v[14:15]
	v_mov_b64_e32 v[32:33], v[16:17]
	s_cbranch_scc1 .LBB0_397
	s_branch .Lgla_top

; #define LAS __attribute__((address_space(3)))
; #define LBAR() do { asm volatile("s_waitcnt lgkmcnt(0)" ::: "memory"); __builtin_amdgcn_s_barrier(); asm volatile("" ::: "memory"); } while (0)
; __device__ void gla_chunk_phase(const Params& p, int l, LAS unsigned char* lds) {
;     ...
;             LBAR();
;             if (tid < 128) *(LAS u32x4*)(dnA + dtok * 40 + dc8) = (u32x4){rd.x, rd.y, rd.z, rd.w};
.Lgla_top:
	s_and_saveexec_b64 s[20:21], s[44:45]
	s_cbranch_execz .LBB0_438
	s_waitcnt vmcnt(1) lgkmcnt(0)
	ds_write_b128 v104, v[6:9]
